# nt hint on P1's shift-image f32 weight loads (w_in / w_ffn_in of layer 0; tasks are spread so no line sharing within a workgroup)
# speedup vs baseline: 1.0124x; 1.0019x over previous
.LBB0_133:
	v_lshl_add_u64 v[14:15], v[20:21], 0, s[40:41]
	v_lshl_add_u64 v[16:17], v[14:15], 0, s[40:41]
	v_lshl_add_u64 v[26:27], v[16:17], 0, s[40:41]
	v_lshl_add_u64 v[28:29], v[26:27], 0, s[40:41]
	v_lshl_add_u64 v[30:31], v[28:29], 0, s[40:41]
	v_lshl_add_u64 v[32:33], v[30:31], 0, s[40:41]
	v_lshl_add_u64 v[34:35], v[32:33], 0, s[40:41]
	v_lshl_add_u64 v[36:37], v[34:35], 0, s[42:43]
	global_load_dword v76, v[20:21], off nt
	global_load_dword v77, v[14:15], off nt
	global_load_dword v78, v[16:17], off nt
	global_load_dword v79, v[26:27], off nt
	global_load_dword v80, v[28:29], off nt
	global_load_dword v81, v[30:31], off nt
	global_load_dword v82, v[32:33], off nt
	global_load_dword v84, v[34:35], off nt
	global_load_dword v75, v[36:37], off nt
	v_lshl_add_u64 v[14:15], v[36:37], 0, s[40:41]
	v_lshl_add_u64 v[16:17], v[14:15], 0, s[40:41]
	global_load_dword v88, v[14:15], off nt
	global_load_dword v89, v[16:17], off nt
	v_lshl_add_u64 v[14:15], v[16:17], 0, s[40:41]
	global_load_dword v91, v[14:15], off nt
	v_lshl_add_u64 v[14:15], v[14:15], 0, s[40:41]
	global_load_dword v116, v[14:15], off nt
	v_lshl_add_u64 v[14:15], v[14:15], 0, s[40:41]
	global_load_dword v117, v[14:15], off nt
	v_lshl_add_u64 v[14:15], v[14:15], 0, s[40:41]
	global_load_dword v118, v[14:15], off nt
	v_lshl_add_u64 v[14:15], v[14:15], 0, s[40:41]
	global_load_dword v119, v[14:15], off nt
	v_lshl_add_u64 v[14:15], v[14:15], 0, s[42:43]
	global_load_dword v67, v[14:15], off nt
	v_lshl_add_u64 v[14:15], v[14:15], 0, s[40:41]
	global_load_dword v68, v[14:15], off nt
	v_lshl_add_u64 v[14:15], v[14:15], 0, s[40:41]
	global_load_dword v69, v[14:15], off nt
	v_lshl_add_u64 v[14:15], v[14:15], 0, s[40:41]
	global_load_dword v70, v[14:15], off nt
	v_lshl_add_u64 v[14:15], v[14:15], 0, s[40:41]
	global_load_dword v71, v[14:15], off nt
	v_lshl_add_u64 v[14:15], v[14:15], 0, s[40:41]
	global_load_dword v72, v[14:15], off nt
	v_lshl_add_u64 v[14:15], v[14:15], 0, s[40:41]
	global_load_dword v73, v[14:15], off nt
	v_lshl_add_u64 v[14:15], v[14:15], 0, s[40:41]
	global_load_dword v74, v[14:15], off nt
	v_lshl_add_u64 v[14:15], v[14:15], 0, s[42:43]
	global_load_dword v59, v[14:15], off nt
	v_lshl_add_u64 v[14:15], v[14:15], 0, s[40:41]
	global_load_dword v60, v[14:15], off nt
	v_lshl_add_u64 v[14:15], v[14:15], 0, s[40:41]
	global_load_dword v61, v[14:15], off nt
	v_lshl_add_u64 v[14:15], v[14:15], 0, s[40:41]
	global_load_dword v62, v[14:15], off nt
	v_lshl_add_u64 v[14:15], v[14:15], 0, s[40:41]
	global_load_dword v63, v[14:15], off nt
	v_lshl_add_u64 v[14:15], v[14:15], 0, s[40:41]
	global_load_dword v64, v[14:15], off nt
	v_lshl_add_u64 v[14:15], v[14:15], 0, s[40:41]
	global_load_dword v65, v[14:15], off nt
	v_lshl_add_u64 v[14:15], v[14:15], 0, s[40:41]
	global_load_dword v66, v[14:15], off nt
	v_lshl_add_u64 v[14:15], v[14:15], 0, s[42:43]
	global_load_dword v51, v[14:15], off nt
	v_lshl_add_u64 v[14:15], v[14:15], 0, s[40:41]
	global_load_dword v52, v[14:15], off nt
	v_lshl_add_u64 v[14:15], v[14:15], 0, s[40:41]
	global_load_dword v53, v[14:15], off nt
	v_lshl_add_u64 v[14:15], v[14:15], 0, s[40:41]
	global_load_dword v54, v[14:15], off nt
	v_lshl_add_u64 v[14:15], v[14:15], 0, s[40:41]
	global_load_dword v55, v[14:15], off nt
	v_lshl_add_u64 v[14:15], v[14:15], 0, s[40:41]
	global_load_dword v56, v[14:15], off nt
	v_lshl_add_u64 v[14:15], v[14:15], 0, s[40:41]
	global_load_dword v57, v[14:15], off nt
	v_lshl_add_u64 v[14:15], v[14:15], 0, s[40:41]
	global_load_dword v58, v[14:15], off nt
	v_lshl_add_u64 v[14:15], v[14:15], 0, s[42:43]
	global_load_dword v43, v[14:15], off nt
	v_lshl_add_u64 v[14:15], v[14:15], 0, s[40:41]
	global_load_dword v44, v[14:15], off nt
	v_lshl_add_u64 v[14:15], v[14:15], 0, s[40:41]
	global_load_dword v45, v[14:15], off nt
	v_lshl_add_u64 v[14:15], v[14:15], 0, s[40:41]
	global_load_dword v46, v[14:15], off nt
	v_lshl_add_u64 v[14:15], v[14:15], 0, s[40:41]
	global_load_dword v47, v[14:15], off nt
	v_lshl_add_u64 v[14:15], v[14:15], 0, s[40:41]
	global_load_dword v48, v[14:15], off nt
	v_lshl_add_u64 v[14:15], v[14:15], 0, s[40:41]
	global_load_dword v49, v[14:15], off nt
	v_lshl_add_u64 v[14:15], v[14:15], 0, s[40:41]
	global_load_dword v50, v[14:15], off nt
	v_lshl_add_u64 v[14:15], v[14:15], 0, s[42:43]
	global_load_dword v35, v[14:15], off nt
	v_lshl_add_u64 v[14:15], v[14:15], 0, s[40:41]
	global_load_dword v36, v[14:15], off nt
	v_lshl_add_u64 v[14:15], v[14:15], 0, s[40:41]
	global_load_dword v37, v[14:15], off nt
	v_lshl_add_u64 v[14:15], v[14:15], 0, s[40:41]
	global_load_dword v38, v[14:15], off nt
	v_lshl_add_u64 v[14:15], v[14:15], 0, s[40:41]
	global_load_dword v39, v[14:15], off nt
	v_lshl_add_u64 v[14:15], v[14:15], 0, s[40:41]
	global_load_dword v40, v[14:15], off nt
	v_lshl_add_u64 v[14:15], v[14:15], 0, s[40:41]
	global_load_dword v41, v[14:15], off nt
	v_lshl_add_u64 v[14:15], v[14:15], 0, s[40:41]
	global_load_dword v42, v[14:15], off nt
	v_lshl_add_u64 v[14:15], v[14:15], 0, s[42:43]
	global_load_dword v25, v[14:15], off nt
	v_lshl_add_u64 v[14:15], v[14:15], 0, s[40:41]
	global_load_dword v26, v[14:15], off nt
	v_lshl_add_u64 v[14:15], v[14:15], 0, s[40:41]
	global_load_dword v27, v[14:15], off nt
	v_lshl_add_u64 v[14:15], v[14:15], 0, s[40:41]
	global_load_dword v28, v[14:15], off nt
	v_lshl_add_u64 v[14:15], v[14:15], 0, s[40:41]
	global_load_dword v29, v[14:15], off nt
	v_lshl_add_u64 v[14:15], v[14:15], 0, s[40:41]
	global_load_dword v30, v[14:15], off nt
	v_lshl_add_u64 v[14:15], v[14:15], 0, s[40:41]
	global_load_dword v31, v[14:15], off nt
	v_lshl_add_u64 v[14:15], v[14:15], 0, s[40:41]
	global_load_dword v32, v[14:15], off nt
	s_waitcnt vmcnt(62)
	v_cvt_pk_bf16_f32 v14, v76, v77
	s_waitcnt vmcnt(60)
	v_cvt_pk_bf16_f32 v15, v78, v79
	s_waitcnt vmcnt(58)
	v_cvt_pk_bf16_f32 v16, v80, v81
	s_waitcnt vmcnt(56)
	v_cvt_pk_bf16_f32 v17, v82, v84
	v_add_u32_e32 v33, v23, v22
	v_add_u32_e32 v34, v24, v22
	v_lshlrev_b32_e32 v85, 16, v14
	v_and_b32_e32 v86, 0xffff0000, v14
	v_lshlrev_b32_e32 v87, 16, v15
	v_and_b32_e32 v92, 0xffff0000, v15
	v_and_b32_e32 v96, 0xffff0000, v17
	v_lshlrev_b32_e32 v93, 16, v16
	v_and_b32_e32 v94, 0xffff0000, v16
	v_lshlrev_b32_e32 v95, 16, v17
	v_add_u32_e32 v97, 0x11220, v33
	v_add_u32_e32 v100, 0x19320, v33
	v_add_u32_e32 v108, 0x11220, v34
	v_sub_f32_e32 v76, v76, v85
	v_sub_f32_e32 v77, v77, v86
	v_sub_f32_e32 v78, v78, v87
	v_sub_f32_e32 v79, v79, v92
	v_sub_f32_e32 v84, v84, v96
	v_sub_f32_e32 v80, v80, v93
	v_sub_f32_e32 v81, v81, v94
	v_sub_f32_e32 v82, v82, v95
	v_cvt_pk_bf16_f32 v76, v76, v77
	v_cvt_pk_bf16_f32 v77, v78, v79
	v_cvt_pk_bf16_f32 v78, v80, v81
	v_cvt_pk_bf16_f32 v79, v82, v84
	ds_read_b128 v[84:87], v33
	ds_read_b128 v[92:95], v33 offset:33024
	ds_read_b128 v[96:99], v97
	ds_read_b128 v[100:103], v100
	ds_read_b128 v[104:107], v34
	ds_read_b128 v[108:111], v108
	s_waitcnt lgkmcnt(5)
	v_mfma_f32_16x16x32_bf16 v[10:13], v[84:87], v[14:17], v[10:13]
	s_waitcnt vmcnt(54)
	v_cvt_pk_bf16_f32 v112, v75, v88
	s_waitcnt vmcnt(52)
	v_cvt_pk_bf16_f32 v113, v89, v91
	s_waitcnt vmcnt(50)
	v_cvt_pk_bf16_f32 v114, v116, v117
	s_waitcnt lgkmcnt(4)
	v_mfma_f32_16x16x32_bf16 v[6:9], v[92:95], v[14:17], v[6:9]
	s_waitcnt vmcnt(48)
	v_cvt_pk_bf16_f32 v115, v118, v119
	v_add_u32_e32 v120, 0x11260, v33
	v_and_b32_e32 v125, 0xffff0000, v115
	s_waitcnt lgkmcnt(1)
	v_mfma_f32_16x16x32_bf16 v[2:5], v[104:107], v[14:17], v[2:5]
	v_lshlrev_b32_e32 v80, 16, v112
	v_and_b32_e32 v81, 0xffff0000, v112
	v_lshlrev_b32_e32 v82, 16, v113
	v_mfma_f32_16x16x32_bf16 v[10:13], v[84:87], v[76:79], v[10:13]
	v_and_b32_e32 v121, 0xffff0000, v113
	v_lshlrev_b32_e32 v122, 16, v114
	v_and_b32_e32 v123, 0xffff0000, v114
	v_lshlrev_b32_e32 v124, 16, v115
	v_sub_f32_e32 v119, v119, v125
	v_mfma_f32_16x16x32_bf16 v[6:9], v[92:95], v[76:79], v[6:9]
	v_sub_f32_e32 v75, v75, v80
	v_sub_f32_e32 v80, v88, v81
	v_sub_f32_e32 v81, v89, v82
	v_mfma_f32_16x16x32_bf16 v[2:5], v[104:107], v[76:79], v[2:5]
	v_sub_f32_e32 v82, v91, v121
	v_sub_f32_e32 v88, v116, v122
	v_sub_f32_e32 v89, v117, v123
	v_sub_f32_e32 v91, v118, v124
	v_cvt_pk_bf16_f32 v116, v75, v80
	v_cvt_pk_bf16_f32 v117, v81, v82
	v_cvt_pk_bf16_f32 v118, v88, v89
	v_cvt_pk_bf16_f32 v119, v91, v119
	ds_read_b128 v[120:123], v120
	ds_read_b128 v[124:127], v33 offset:64
	ds_read_b128 v[128:131], v33 offset:33088
	v_mfma_f32_16x16x32_bf16 v[10:13], v[96:99], v[14:17], v[10:13]
	v_add_u32_e32 v132, 0x19360, v33
	v_add_u32_e32 v140, 0x11260, v34
	ds_read_b128 v[132:135], v132
	ds_read_b128 v[136:139], v34 offset:64
	ds_read_b128 v[140:143], v140
	v_mfma_f32_16x16x32_bf16 v[6:9], v[100:103], v[14:17], v[6:9]
	s_waitcnt vmcnt(46)
	v_cvt_pk_bf16_f32 v84, v67, v68
	s_waitcnt vmcnt(44)
	v_cvt_pk_bf16_f32 v85, v69, v70
	s_waitcnt vmcnt(42)
	v_cvt_pk_bf16_f32 v86, v71, v72
	s_waitcnt lgkmcnt(6)
	v_mfma_f32_16x16x32_bf16 v[2:5], v[108:111], v[14:17], v[2:5]
	s_waitcnt vmcnt(40)
	v_cvt_pk_bf16_f32 v87, v73, v74
	v_and_b32_e32 v80, 0xffff0000, v84
	v_lshlrev_b32_e32 v76, 16, v85
	s_waitcnt lgkmcnt(4)
	v_mfma_f32_16x16x32_bf16 v[10:13], v[124:127], v[112:115], v[10:13]
	v_and_b32_e32 v77, 0xffff0000, v85
	v_lshlrev_b32_e32 v78, 16, v86
	v_and_b32_e32 v79, 0xffff0000, v86
	s_waitcnt lgkmcnt(3)
	v_mfma_f32_16x16x32_bf16 v[6:9], v[128:131], v[112:115], v[6:9]
	v_lshlrev_b32_e32 v81, 16, v87
	v_and_b32_e32 v82, 0xffff0000, v87
	v_add_u32_e32 v144, 0x112a0, v33
	s_waitcnt lgkmcnt(1)
	v_mfma_f32_16x16x32_bf16 v[2:5], v[136:139], v[112:115], v[2:5]
	v_lshlrev_b32_e32 v75, 16, v84
	v_sub_f32_e32 v68, v68, v80
	v_sub_f32_e32 v69, v69, v76
	v_mfma_f32_16x16x32_bf16 v[10:13], v[124:127], v[116:119], v[10:13]
	v_sub_f32_e32 v15, v70, v77
	v_sub_f32_e32 v16, v71, v78
	v_sub_f32_e32 v17, v72, v79
	v_sub_f32_e32 v70, v73, v81
	v_sub_f32_e32 v71, v74, v82
	v_mfma_f32_16x16x32_bf16 v[6:9], v[128:131], v[116:119], v[6:9]
	v_sub_f32_e32 v67, v67, v75
	v_cvt_pk_bf16_f32 v14, v67, v68
	v_cvt_pk_bf16_f32 v15, v69, v15
	v_mfma_f32_16x16x32_bf16 v[2:5], v[136:139], v[116:119], v[2:5]
	v_cvt_pk_bf16_f32 v16, v16, v17
	v_cvt_pk_bf16_f32 v17, v70, v71
	ds_read_b128 v[68:71], v144
	ds_read_b128 v[72:75], v33 offset:128
	ds_read_b128 v[76:79], v33 offset:33152
	v_mfma_f32_16x16x32_bf16 v[10:13], v[120:123], v[112:115], v[10:13]
	v_add_u32_e32 v145, 0x193a0, v33
	v_add_u32_e32 v146, 0x112a0, v34
	ds_read_b128 v[92:95], v145
	ds_read_b128 v[96:99], v34 offset:128
	ds_read_b128 v[100:103], v146
	v_mfma_f32_16x16x32_bf16 v[6:9], v[132:135], v[112:115], v[6:9]
	s_waitcnt vmcnt(38)
	v_cvt_pk_bf16_f32 v104, v59, v60
	s_waitcnt vmcnt(36)
	v_cvt_pk_bf16_f32 v105, v61, v62
	s_waitcnt vmcnt(34)
	v_cvt_pk_bf16_f32 v106, v63, v64
	s_waitcnt lgkmcnt(6)
	v_mfma_f32_16x16x32_bf16 v[2:5], v[140:143], v[112:115], v[2:5]
	s_waitcnt vmcnt(32)
	v_cvt_pk_bf16_f32 v107, v65, v66
	v_and_b32_e32 v80, 0xffff0000, v104
	v_lshlrev_b32_e32 v81, 16, v105
	s_waitcnt lgkmcnt(4)
	v_mfma_f32_16x16x32_bf16 v[10:13], v[72:75], v[84:87], v[10:13]
	v_and_b32_e32 v82, 0xffff0000, v105
	v_lshlrev_b32_e32 v88, 16, v106
	v_and_b32_e32 v89, 0xffff0000, v106
	s_waitcnt lgkmcnt(3)
	v_mfma_f32_16x16x32_bf16 v[6:9], v[76:79], v[84:87], v[6:9]
	v_lshlrev_b32_e32 v91, 16, v107
	v_and_b32_e32 v108, 0xffff0000, v107
	v_add_u32_e32 v147, 0x112e0, v33
	s_waitcnt lgkmcnt(1)
	v_mfma_f32_16x16x32_bf16 v[2:5], v[96:99], v[84:87], v[2:5]
	v_lshlrev_b32_e32 v67, 16, v104
	v_sub_f32_e32 v60, v60, v80
	v_sub_f32_e32 v61, v61, v81
	v_mfma_f32_16x16x32_bf16 v[10:13], v[72:75], v[14:17], v[10:13]
	v_sub_f32_e32 v62, v62, v82
	v_sub_f32_e32 v63, v63, v88
	v_sub_f32_e32 v64, v64, v89
	v_sub_f32_e32 v65, v65, v91
	v_sub_f32_e32 v66, v66, v108
	v_mfma_f32_16x16x32_bf16 v[6:9], v[76:79], v[14:17], v[6:9]
	v_sub_f32_e32 v59, v59, v67
	v_cvt_pk_bf16_f32 v60, v59, v60
	v_cvt_pk_bf16_f32 v61, v61, v62
	v_mfma_f32_16x16x32_bf16 v[2:5], v[96:99], v[14:17], v[2:5]
	v_cvt_pk_bf16_f32 v62, v63, v64
	v_cvt_pk_bf16_f32 v63, v65, v66
	ds_read_b128 v[64:67], v147
	ds_read_b128 v[72:75], v33 offset:192
	ds_read_b128 v[108:111], v33 offset:33216
	v_mfma_f32_16x16x32_bf16 v[10:13], v[68:71], v[84:87], v[10:13]
	v_add_u32_e32 v148, 0x193e0, v33
	v_add_u32_e32 v149, 0x112e0, v34
	ds_read_b128 v[76:79], v148
	ds_read_b128 v[112:115], v34 offset:192
	ds_read_b128 v[116:119], v149
	v_mfma_f32_16x16x32_bf16 v[6:9], v[92:95], v[84:87], v[6:9]
	s_waitcnt vmcnt(30)
	v_cvt_pk_bf16_f32 v14, v51, v52
	s_waitcnt vmcnt(28)
	v_cvt_pk_bf16_f32 v15, v53, v54
	s_waitcnt vmcnt(26)
	v_cvt_pk_bf16_f32 v16, v55, v56
	s_waitcnt lgkmcnt(6)
	v_mfma_f32_16x16x32_bf16 v[2:5], v[100:103], v[84:87], v[2:5]
	s_waitcnt vmcnt(24)
	v_cvt_pk_bf16_f32 v17, v57, v58
	v_and_b32_e32 v68, 0xffff0000, v14
	v_lshlrev_b32_e32 v69, 16, v15
	s_waitcnt lgkmcnt(4)
	v_mfma_f32_16x16x32_bf16 v[10:13], v[72:75], v[104:107], v[10:13]
	v_and_b32_e32 v70, 0xffff0000, v15
	v_lshlrev_b32_e32 v71, 16, v16
	v_and_b32_e32 v80, 0xffff0000, v16
	s_waitcnt lgkmcnt(3)
	v_mfma_f32_16x16x32_bf16 v[6:9], v[108:111], v[104:107], v[6:9]
	v_lshlrev_b32_e32 v81, 16, v17
	v_and_b32_e32 v82, 0xffff0000, v17
	v_add_u32_e32 v150, 0x11320, v33
	s_waitcnt lgkmcnt(1)
	v_mfma_f32_16x16x32_bf16 v[2:5], v[112:115], v[104:107], v[2:5]
	v_lshlrev_b32_e32 v59, 16, v14
	v_sub_f32_e32 v52, v52, v68
	v_sub_f32_e32 v53, v53, v69
	v_mfma_f32_16x16x32_bf16 v[10:13], v[72:75], v[60:63], v[10:13]
	v_sub_f32_e32 v54, v54, v70
	v_sub_f32_e32 v55, v55, v71
	v_sub_f32_e32 v56, v56, v80
	v_sub_f32_e32 v57, v57, v81
	v_sub_f32_e32 v58, v58, v82
	v_mfma_f32_16x16x32_bf16 v[6:9], v[108:111], v[60:63], v[6:9]
	v_sub_f32_e32 v51, v51, v59
	v_cvt_pk_bf16_f32 v52, v51, v52
	v_cvt_pk_bf16_f32 v53, v53, v54
	v_mfma_f32_16x16x32_bf16 v[2:5], v[112:115], v[60:63], v[2:5]
	v_cvt_pk_bf16_f32 v54, v55, v56
	v_cvt_pk_bf16_f32 v55, v57, v58
	ds_read_b128 v[56:59], v150
	ds_read_b128 v[68:71], v33 offset:256
	ds_read_b128 v[72:75], v33 offset:33280
	v_mfma_f32_16x16x32_bf16 v[10:13], v[64:67], v[104:107], v[10:13]
	v_add_u32_e32 v151, 0x19420, v33
	v_add_u32_e32 v152, 0x11320, v34
	ds_read_b128 v[60:63], v151
	ds_read_b128 v[84:87], v34 offset:256
	ds_read_b128 v[92:95], v152
	v_mfma_f32_16x16x32_bf16 v[6:9], v[76:79], v[104:107], v[6:9]
	s_waitcnt vmcnt(22)
	v_cvt_pk_bf16_f32 v64, v43, v44
	s_waitcnt vmcnt(20)
	v_cvt_pk_bf16_f32 v65, v45, v46
	s_waitcnt vmcnt(18)
	v_cvt_pk_bf16_f32 v66, v47, v48
	s_waitcnt lgkmcnt(6)
	v_mfma_f32_16x16x32_bf16 v[2:5], v[116:119], v[104:107], v[2:5]
	s_waitcnt vmcnt(16)
	v_cvt_pk_bf16_f32 v67, v49, v50
	v_and_b32_e32 v76, 0xffff0000, v64
	v_lshlrev_b32_e32 v77, 16, v65
	s_waitcnt lgkmcnt(4)
	v_mfma_f32_16x16x32_bf16 v[10:13], v[68:71], v[14:17], v[10:13]
	v_and_b32_e32 v78, 0xffff0000, v65
	v_lshlrev_b32_e32 v79, 16, v66
	v_and_b32_e32 v80, 0xffff0000, v66
	s_waitcnt lgkmcnt(3)
	v_mfma_f32_16x16x32_bf16 v[6:9], v[72:75], v[14:17], v[6:9]
	v_lshlrev_b32_e32 v81, 16, v67
	v_and_b32_e32 v82, 0xffff0000, v67
	v_add_u32_e32 v153, 0x11360, v33
	s_waitcnt lgkmcnt(1)
	v_mfma_f32_16x16x32_bf16 v[2:5], v[84:87], v[14:17], v[2:5]
	v_lshlrev_b32_e32 v51, 16, v64
	v_sub_f32_e32 v44, v44, v76
	v_sub_f32_e32 v45, v45, v77
	v_mfma_f32_16x16x32_bf16 v[10:13], v[68:71], v[52:55], v[10:13]
	v_sub_f32_e32 v46, v46, v78
	v_sub_f32_e32 v47, v47, v79
	v_sub_f32_e32 v48, v48, v80
	v_sub_f32_e32 v49, v49, v81
	v_sub_f32_e32 v50, v50, v82
	v_mfma_f32_16x16x32_bf16 v[6:9], v[72:75], v[52:55], v[6:9]
	v_sub_f32_e32 v43, v43, v51
	v_cvt_pk_bf16_f32 v44, v43, v44
	v_cvt_pk_bf16_f32 v45, v45, v46
	v_mfma_f32_16x16x32_bf16 v[2:5], v[84:87], v[52:55], v[2:5]
	v_cvt_pk_bf16_f32 v46, v47, v48
	v_cvt_pk_bf16_f32 v47, v49, v50
	ds_read_b128 v[48:51], v153
	ds_read_b128 v[52:55], v33 offset:320
	ds_read_b128 v[68:71], v33 offset:33344
	v_mfma_f32_16x16x32_bf16 v[10:13], v[56:59], v[14:17], v[10:13]
	v_add_u32_e32 v154, 0x19460, v33
	v_add_u32_e32 v155, 0x11360, v34
	ds_read_b128 v[56:59], v154
	ds_read_b128 v[72:75], v34 offset:320
	ds_read_b128 v[76:79], v155
	v_mfma_f32_16x16x32_bf16 v[6:9], v[60:63], v[14:17], v[6:9]
	s_waitcnt vmcnt(14)
	v_cvt_pk_bf16_f32 v60, v35, v36
	s_waitcnt vmcnt(12)
	v_cvt_pk_bf16_f32 v61, v37, v38
	s_waitcnt vmcnt(10)
	v_cvt_pk_bf16_f32 v62, v39, v40
	s_waitcnt lgkmcnt(6)
	v_mfma_f32_16x16x32_bf16 v[2:5], v[92:95], v[14:17], v[2:5]
	s_waitcnt vmcnt(8)
	v_cvt_pk_bf16_f32 v63, v41, v42
	v_lshlrev_b32_e32 v14, 16, v60
	v_and_b32_e32 v15, 0xffff0000, v60
	s_waitcnt lgkmcnt(4)
	v_mfma_f32_16x16x32_bf16 v[10:13], v[52:55], v[64:67], v[10:13]
	v_lshlrev_b32_e32 v16, 16, v61
	v_and_b32_e32 v17, 0xffff0000, v61
	v_and_b32_e32 v80, 0xffff0000, v62
	s_waitcnt lgkmcnt(3)
	v_mfma_f32_16x16x32_bf16 v[6:9], v[68:71], v[64:67], v[6:9]
	v_lshlrev_b32_e32 v81, 16, v63
	v_and_b32_e32 v82, 0xffff0000, v63
	v_add_u32_e32 v156, 0x113a0, v33
	s_waitcnt lgkmcnt(1)
	v_mfma_f32_16x16x32_bf16 v[2:5], v[72:75], v[64:67], v[2:5]
	v_lshlrev_b32_e32 v43, 16, v62
	v_sub_f32_e32 v14, v35, v14
	v_sub_f32_e32 v15, v36, v15
	v_mfma_f32_16x16x32_bf16 v[10:13], v[52:55], v[44:47], v[10:13]
	v_sub_f32_e32 v16, v37, v16
	v_sub_f32_e32 v17, v38, v17
	v_sub_f32_e32 v36, v40, v80
	v_mfma_f32_16x16x32_bf16 v[6:9], v[68:71], v[44:47], v[6:9]
	v_sub_f32_e32 v37, v41, v81
	v_sub_f32_e32 v38, v42, v82
	v_sub_f32_e32 v35, v39, v43
	v_mfma_f32_16x16x32_bf16 v[2:5], v[72:75], v[44:47], v[2:5]
	v_cvt_pk_bf16_f32 v14, v14, v15
	v_cvt_pk_bf16_f32 v15, v16, v17
	v_cvt_pk_bf16_f32 v16, v35, v36
	v_cvt_pk_bf16_f32 v17, v37, v38
	v_mfma_f32_16x16x32_bf16 v[10:13], v[48:51], v[64:67], v[10:13]
	ds_read_b128 v[36:39], v156
	ds_read_b128 v[40:43], v33 offset:384
	ds_read_b128 v[44:47], v33 offset:33408
	v_add_u32_e32 v157, 0x194a0, v33
	v_add_u32_e32 v158, 0x113a0, v34
	v_mfma_f32_16x16x32_bf16 v[6:9], v[56:59], v[64:67], v[6:9]
	ds_read_b128 v[48:51], v157
	ds_read_b128 v[52:55], v34 offset:384
	ds_read_b128 v[56:59], v158
	s_waitcnt lgkmcnt(6)
	v_mfma_f32_16x16x32_bf16 v[2:5], v[76:79], v[64:67], v[2:5]
	s_waitcnt vmcnt(6)
	v_cvt_pk_bf16_f32 v64, v25, v26
	s_waitcnt vmcnt(4)
	v_cvt_pk_bf16_f32 v65, v27, v28
	s_waitcnt vmcnt(2)
	v_cvt_pk_bf16_f32 v66, v29, v30
	s_waitcnt lgkmcnt(4)
	v_mfma_f32_16x16x32_bf16 v[10:13], v[40:43], v[60:63], v[10:13]
	s_waitcnt vmcnt(0)
	v_cvt_pk_bf16_f32 v67, v31, v32
	v_and_b32_e32 v68, 0xffff0000, v64
	v_lshlrev_b32_e32 v69, 16, v65
	s_waitcnt lgkmcnt(3)
	v_mfma_f32_16x16x32_bf16 v[6:9], v[44:47], v[60:63], v[6:9]
	v_and_b32_e32 v70, 0xffff0000, v65
	v_lshlrev_b32_e32 v71, 16, v66
	v_lshlrev_b32_e32 v73, 16, v67
	s_waitcnt lgkmcnt(1)
	v_mfma_f32_16x16x32_bf16 v[2:5], v[52:55], v[60:63], v[2:5]
	v_lshlrev_b32_e32 v35, 16, v64
	v_and_b32_e32 v72, 0xffff0000, v66
	v_and_b32_e32 v74, 0xffff0000, v67
	v_mfma_f32_16x16x32_bf16 v[10:13], v[40:43], v[14:17], v[10:13]
	v_sub_f32_e32 v26, v26, v68
	v_sub_f32_e32 v27, v27, v69
	v_sub_f32_e32 v28, v28, v70
	v_mfma_f32_16x16x32_bf16 v[6:9], v[44:47], v[14:17], v[6:9]
	v_sub_f32_e32 v29, v29, v71
	v_sub_f32_e32 v25, v25, v35
	v_sub_f32_e32 v30, v30, v72
	v_mfma_f32_16x16x32_bf16 v[2:5], v[52:55], v[14:17], v[2:5]
	v_sub_f32_e32 v17, v31, v73
	v_sub_f32_e32 v31, v32, v74
	v_cvt_pk_bf16_f32 v14, v25, v26
	v_mfma_f32_16x16x32_bf16 v[10:13], v[36:39], v[60:63], v[10:13]
	v_cvt_pk_bf16_f32 v15, v27, v28
	v_cvt_pk_bf16_f32 v16, v29, v30
	v_cvt_pk_bf16_f32 v17, v17, v31
	ds_read_b128 v[26:29], v33 offset:448
	ds_read_b128 v[36:39], v33 offset:33472
	ds_read_b128 v[40:43], v34 offset:448
	v_mfma_f32_16x16x32_bf16 v[6:9], v[48:51], v[60:63], v[6:9]
	v_add_u32_e32 v25, 0x113e0, v33
	v_add_u32_e32 v30, 0x194e0, v33
	s_waitcnt lgkmcnt(3)
	v_mfma_f32_16x16x32_bf16 v[2:5], v[56:59], v[60:63], v[2:5]
	s_waitcnt lgkmcnt(2)
	v_mfma_f32_16x16x32_bf16 v[10:13], v[26:29], v[64:67], v[10:13]
	s_waitcnt lgkmcnt(1)
	v_mfma_f32_16x16x32_bf16 v[6:9], v[36:39], v[64:67], v[6:9]
	s_waitcnt lgkmcnt(0)
	v_mfma_f32_16x16x32_bf16 v[2:5], v[40:43], v[64:67], v[2:5]
	v_mfma_f32_16x16x32_bf16 v[10:13], v[26:29], v[14:17], v[10:13]
	ds_read_b128 v[26:29], v25
	v_mfma_f32_16x16x32_bf16 v[6:9], v[36:39], v[14:17], v[6:9]
	v_mfma_f32_16x16x32_bf16 v[2:5], v[40:43], v[14:17], v[2:5]
	ds_read_b128 v[14:17], v30
	v_add_u32_e32 v25, 0x113e0, v34
	s_waitcnt lgkmcnt(0)
	v_mfma_f32_16x16x32_bf16 v[6:9], v[14:17], v[64:67], v[6:9]
	ds_read_b128 v[14:17], v25
	v_mfma_f32_16x16x32_bf16 v[10:13], v[26:29], v[64:67], v[10:13]
	s_waitcnt lgkmcnt(0)
	v_mfma_f32_16x16x32_bf16 v[2:5], v[14:17], v[64:67], v[2:5]
	s_add_i32 s4, s4, 8
	v_add_u32_e32 v23, 0x200, v23
	v_add_u32_e32 v24, 0x200, v24
	s_cmp_gt_u32 s4, 23
	v_lshl_add_u64 v[20:21], v[20:21], 0, s[24:25]
	s_cbranch_scc0 .LBB0_133
	v_lshlrev_b32_e32 v82, 2, v18
	v_lshlrev_b32_e32 v16, 2, v19
	v_cmp_gt_i32_e32 vcc, 9, v19
	v_lshl_add_u64 v[14:15], s[38:39], 0, v[82:83]
	s_and_saveexec_b64 s[4:5], vcc
	s_cbranch_execz .LBB0_136
	v_mad_i64_i32 v[20:21], s[6:7], v16, s62, 0
	v_add_f32_e32 v10, 0, v10
	v_lshl_add_u64 v[20:21], v[20:21], 2, v[14:15]
	global_store_dword v[20:21], v10, off
